# halo_fix loop unrolled 3x with all loads requested up front (counted vmcnt per trip)
# speedup vs baseline: 1.0029x; 1.0029x over previous
; __device__ __forceinline__ void halo_fix(const Params& p, int pm, int tid, int tail_first) {
;     const float* HB = (const float*)(p.ws + WS_HALO); const float* H = HB + (size_t)pm * 6 * FFN; bf16* ACT = (bf16*)(p.ws + WS_ACT);
;     const f32x4 z4 = (f32x4){0.f, 0.f, 0.f, 0.f};
;     for (int q = tid; q < FFN / 4; q += NTHREADS) { const int ch = 4 * q;
;         const f32x4 w0 = *(const f32x4*)(p.conv_w + ch), w1 = *(const f32x4*)(p.conv_w + FFN + ch), w2 = *(const f32x4*)(p.conv_w + 2 * FFN + ch), cbv = *(const f32x4*)(p.conv_b + ch);
;         const f32x4 pv = (pm & 7) ? *(const f32x4*)(HB + ((size_t)(pm - 1) * 6 + 3) * FFN + ch) : z4; const f32x4 nx = ((pm & 7) != 7) ? *(const f32x4*)(HB + ((size_t)(pm + 1) * 6 + 0) * FFN + ch) : z4;
;         const f32x4 h0 = *(const f32x4*)(H + ch), h1 = *(const f32x4*)(H + FFN + ch), h2 = *(const f32x4*)(H + 2 * FFN + ch), h3 = *(const f32x4*)(H + 3 * FFN + ch), h4 = *(const f32x4*)(H + 4 * FFN + ch), h5 = *(const f32x4*)(H + 5 * FFN + ch);
.LBB0_986:
	s_mul_hi_i32 s25, s68, 0x8400
	s_mul_i32 s24, s68, 0x8400
	s_and_saveexec_b64 s[26:27], s[0:1]
	s_cbranch_execz .LBB0_993
	s_lshl_b64 s[28:29], s[24:25], 2
	s_add_u32 s28, s4, s28
	s_addc_u32 s29, s5, s29
	s_and_b32 s36, s68, 7
	s_cmp_lg_u32 s36, 0
	s_mul_i32 s38, s68, 0x21000
	s_cselect_b64 s[30:31], -1, 0
	s_add_i32 s34, s68, -1
	s_add_i32 s35, s38, 0xfffdf000
	s_mul_hi_i32 s34, s34, 0x21000
	s_add_u32 s35, s4, s35
	s_addc_u32 s37, s5, s34
	s_add_u32 s34, s35, 0x10800
	s_addc_u32 s35, s37, 0
	s_cmp_lg_u32 s36, 7
	s_cselect_b64 s[36:37], -1, 0
	s_add_i32 s39, s68, 1
	s_add_i32 s38, s38, 0x21000
	s_mul_hi_i32 s39, s39, 0x21000
	s_add_u32 s38, s4, s38
	s_addc_u32 s39, s5, s39
	s_add_u32 s40, s28, 0x5800
	s_addc_u32 s41, s29, 0
	s_add_u32 s42, s28, 0xb000
	s_addc_u32 s43, s29, 0
	s_add_u32 s44, s28, 0x10800
	s_addc_u32 s45, s29, 0
	s_add_u32 s46, s28, 0x16000
	s_addc_u32 s47, s29, 0
	s_add_u32 s48, s28, 0x1b800
	s_addc_u32 s49, s29, 0
	s_lshl_b32 s52, s68, 8
	s_mul_i32 s50, s68, 0x2c0000
	s_mul_hi_i32 s51, s52, 0x2c00
	s_add_u32 s50, s57, s50
	s_addc_u32 s51, s58, s51
	s_or_b32 s52, s52, 0xff
	s_mul_hi_i32 s53, s52, 0x2c00
	s_mulk_i32 s52, 0x2c00
	s_add_u32 s52, s57, s52
	s_addc_u32 s53, s58, s53
	s_mov_b64 s[54:55], 0
	v_mov_b32_e32 v32, v38
	v_mov_b32_e32 v24, v40
	v_ashrrev_i32_e32 v33, 31, v32
	v_lshlrev_b64 v[34:35], 2, v[32:33]
	v_lshl_add_u64 v[0:1], s[16:17], 0, v[34:35]
	v_lshl_add_u64 v[2:3], s[10:11], 0, v[34:35]
	global_load_dwordx4 v[8:11], v[0:1], off
	global_load_dwordx4 v[16:19], v[2:3], off
	v_lshl_add_u64 v[0:1], s[22:23], 0, v[34:35]
	global_load_dwordx4 v[4:7], v[0:1], off
	v_lshl_add_u64 v[0:1], s[18:19], 0, v[34:35]
	global_load_dwordx4 v[0:3], v[0:1], off
	v_mov_b32_e32 v12, 0
	s_andn2_b64 vcc, exec, s[30:31]
	v_mov_b32_e32 v20, 0
	v_mov_b32_e32 v21, 0
	v_mov_b32_e32 v22, 0
	v_mov_b32_e32 v23, 0
	s_cbranch_vccnz .Lhf_991_0
	v_lshl_add_u64 v[14:15], v[32:33], 2, s[34:35]
	global_load_dwordx4 v[20:23], v[14:15], off

; __device__ __forceinline__ unsigned pk2(float lo, float hi) { const f32x2_t v = {lo, hi}; const bf16x2_t b = __builtin_convertvector(v, bf16x2_t); return __builtin_bit_cast(unsigned, b); }
; __device__ __forceinline__ void halo_fix(const Params& p, int pm, int tid, int tail_first) {
;     ...
;     for (int q = tid; q < FFN / 4; q += NTHREADS) { const int ch = 4 * q;
;         const f32x4 w0 = *(const f32x4*)(p.conv_w + ch), w1 = *(const f32x4*)(p.conv_w + FFN + ch), w2 = *(const f32x4*)(p.conv_w + 2 * FFN + ch), cbv = *(const f32x4*)(p.conv_b + ch);
;         const f32x4 pv = (pm & 7) ? *(const f32x4*)(HB + ((size_t)(pm - 1) * 6 + 3) * FFN + ch) : z4; const f32x4 nx = ((pm & 7) != 7) ? *(const f32x4*)(HB + ((size_t)(pm + 1) * 6 + 0) * FFN + ch) : z4;
;         const f32x4 h0 = *(const f32x4*)(H + ch), h1 = *(const f32x4*)(H + FFN + ch), h2 = *(const f32x4*)(H + 2 * FFN + ch), h3 = *(const f32x4*)(H + 3 * FFN + ch), h4 = *(const f32x4*)(H + 4 * FFN + ch), h5 = *(const f32x4*)(H + 5 * FFN + ch);
;         const f32x4 rt = halo_act4(w0, w1, w2, cbv, pv, h0, h1, h4), rb = halo_act4(w0, w1, w2, cbv, h2, h3, nx, h5);
;         u32x2 ot, ob; ot.x = pk2(rt.x, rt.y); ot.y = pk2(rt.z, rt.w); ob.x = pk2(rb.x, rb.y); ob.y = pk2(rb.z, rb.w);
;         *(u32x2*)(ACT + (size_t)(pm * 256) * FFN + ch) = ot; *(u32x2*)(ACT + (size_t)(pm * 256 + 255) * FFN + ch) = ob;
;     }
.Lhf_h0:
	v_lshl_add_u64 v[42:43], s[28:29], 0, v[34:35]
	global_load_dwordx4 v[42:45], v[42:43], off
	v_lshl_add_u64 v[46:47], s[44:45], 0, v[34:35]
	global_load_dwordx4 v[46:49], v[46:47], off
	v_lshl_add_u64 v[50:51], s[42:43], 0, v[34:35]
	v_lshl_add_u64 v[54:55], s[40:41], 0, v[34:35]
	global_load_dwordx4 v[50:53], v[50:51], off
	v_lshl_add_u64 v[58:59], s[46:47], 0, v[34:35]
	global_load_dwordx4 v[54:57], v[54:55], off
	v_lshl_add_u64 v[34:35], s[48:49], 0, v[34:35]
	global_load_dwordx4 v[58:61], v[58:59], off
	v_add_u32_e32 v24, 0x200, v24
	global_load_dwordx4 v[62:65], v[34:35], off
	v_lshlrev_b64 v[34:35], 1, v[32:33]
	v_cmp_lt_i32_e32 vcc, s62, v24
	v_lshl_add_u64 v[66:67], s[50:51], 0, v[34:35]
	s_or_b64 s[54:55], vcc, s[54:55]
	v_add_u32_e32 v32, 0x800, v32
	v_lshl_add_u64 v[34:35], s[52:53], 0, v[34:35]
	s_mov_b64 s[78:79], exec
	s_andn2_b64 exec, exec, s[54:55]
	s_cbranch_execz .Lhf_c1x
	v_ashrrev_i32_e32 v33, 31, v32
	v_lshlrev_b64 v[134:135], 2, v[32:33]
	v_lshl_add_u64 v[100:101], s[16:17], 0, v[134:135]
	v_lshl_add_u64 v[102:103], s[10:11], 0, v[134:135]
	global_load_dwordx4 v[108:111], v[100:101], off
	global_load_dwordx4 v[116:119], v[102:103], off
	v_lshl_add_u64 v[100:101], s[22:23], 0, v[134:135]
	global_load_dwordx4 v[104:107], v[100:101], off
	v_lshl_add_u64 v[100:101], s[18:19], 0, v[134:135]
	global_load_dwordx4 v[100:103], v[100:101], off
	v_mov_b32_e32 v112, 0
	s_andn2_b64 vcc, exec, s[30:31]
	v_mov_b32_e32 v120, 0
	v_mov_b32_e32 v121, 0
	v_mov_b32_e32 v122, 0
	v_mov_b32_e32 v123, 0
	s_cbranch_vccnz .Lhf_991_1
	v_lshl_add_u64 v[114:115], v[32:33], 2, s[34:35]
	global_load_dwordx4 v[120:123], v[114:115], off
.Lhf_991_1:
	s_andn2_b64 vcc, exec, s[36:37]
	v_mov_b32_e32 v113, 0
	v_mov_b32_e32 v114, 0
	v_mov_b32_e32 v115, 0
	s_cbranch_vccnz .Lhf_h1
	v_lshl_add_u64 v[112:113], v[32:33], 2, s[38:39]
	global_load_dwordx4 v[112:115], v[112:113], off
.Lhf_h1:
	v_lshl_add_u64 v[142:143], s[28:29], 0, v[134:135]
	global_load_dwordx4 v[142:145], v[142:143], off
	v_lshl_add_u64 v[146:147], s[44:45], 0, v[134:135]
	global_load_dwordx4 v[146:149], v[146:147], off
	v_lshl_add_u64 v[150:151], s[42:43], 0, v[134:135]
	v_lshl_add_u64 v[154:155], s[40:41], 0, v[134:135]
	global_load_dwordx4 v[150:153], v[150:151], off
	v_lshl_add_u64 v[158:159], s[46:47], 0, v[134:135]
	global_load_dwordx4 v[154:157], v[154:155], off
	v_lshl_add_u64 v[134:135], s[48:49], 0, v[134:135]
	global_load_dwordx4 v[158:161], v[158:159], off
	v_add_u32_e32 v24, 0x200, v24
	global_load_dwordx4 v[162:165], v[134:135], off
	v_lshlrev_b64 v[134:135], 1, v[32:33]
	v_cmp_lt_i32_e32 vcc, s62, v24
	v_lshl_add_u64 v[166:167], s[50:51], 0, v[134:135]
	s_or_b64 s[54:55], vcc, s[54:55]
	v_add_u32_e32 v32, 0x800, v32
	v_lshl_add_u64 v[134:135], s[52:53], 0, v[134:135]
	s_mov_b64 s[80:81], exec
	s_andn2_b64 exec, exec, s[54:55]
	s_cbranch_execz .Lhf_c2x
	v_ashrrev_i32_e32 v33, 31, v32
	v_lshlrev_b64 v[204:205], 2, v[32:33]
	v_lshl_add_u64 v[170:171], s[16:17], 0, v[204:205]
	v_lshl_add_u64 v[172:173], s[10:11], 0, v[204:205]
	global_load_dwordx4 v[178:181], v[170:171], off
	global_load_dwordx4 v[186:189], v[172:173], off
	v_lshl_add_u64 v[170:171], s[22:23], 0, v[204:205]
	global_load_dwordx4 v[174:177], v[170:171], off
	v_lshl_add_u64 v[170:171], s[18:19], 0, v[204:205]
	global_load_dwordx4 v[170:173], v[170:171], off
	v_mov_b32_e32 v182, 0
	s_andn2_b64 vcc, exec, s[30:31]
	v_mov_b32_e32 v190, 0
	v_mov_b32_e32 v191, 0
	v_mov_b32_e32 v192, 0
	v_mov_b32_e32 v193, 0
	s_cbranch_vccnz .Lhf_991_2
	v_lshl_add_u64 v[184:185], v[32:33], 2, s[34:35]
	global_load_dwordx4 v[190:193], v[184:185], off
.Lhf_991_2:
	s_andn2_b64 vcc, exec, s[36:37]
	v_mov_b32_e32 v183, 0
	v_mov_b32_e32 v184, 0
	v_mov_b32_e32 v185, 0
	s_cbranch_vccnz .Lhf_h2
	v_lshl_add_u64 v[182:183], v[32:33], 2, s[38:39]
	global_load_dwordx4 v[182:185], v[182:183], off
.Lhf_h2:
	v_lshl_add_u64 v[212:213], s[28:29], 0, v[204:205]
	global_load_dwordx4 v[212:215], v[212:213], off
	v_lshl_add_u64 v[216:217], s[44:45], 0, v[204:205]
	global_load_dwordx4 v[216:219], v[216:217], off
	v_lshl_add_u64 v[220:221], s[42:43], 0, v[204:205]
	v_lshl_add_u64 v[224:225], s[40:41], 0, v[204:205]
	global_load_dwordx4 v[220:223], v[220:221], off
	v_lshl_add_u64 v[228:229], s[46:47], 0, v[204:205]
	global_load_dwordx4 v[224:227], v[224:225], off
	v_lshl_add_u64 v[204:205], s[48:49], 0, v[204:205]
	global_load_dwordx4 v[228:231], v[228:229], off
	v_add_u32_e32 v24, 0x200, v24
	global_load_dwordx4 v[232:235], v[204:205], off
	v_lshlrev_b64 v[204:205], 1, v[32:33]
	v_cmp_lt_i32_e32 vcc, s62, v24
	v_lshl_add_u64 v[236:237], s[50:51], 0, v[204:205]
	s_or_b64 s[54:55], vcc, s[54:55]
	v_add_u32_e32 v32, 0x800, v32
	v_lshl_add_u64 v[204:205], s[52:53], 0, v[204:205]
	s_mov_b64 s[82:83], exec
	s_mov_b64 exec, s[78:79]
	s_waitcnt vmcnt(20)
; __device__ __forceinline__ unsigned pk2(float lo, float hi) { const f32x2_t v = {lo, hi}; const bf16x2_t b = __builtin_convertvector(v, bf16x2_t); return __builtin_bit_cast(unsigned, b); }
; __device__ __forceinline__ float siluf_(float x) { return x * __builtin_amdgcn_rcpf(1.0f + __expf(-x)); }
; __device__ __forceinline__ f32x4 halo_act4(const f32x4 w0, const f32x4 w1, const f32x4 w2, const f32x4 cbv, const f32x4 am, const f32x4 a0, const f32x4 ap, const f32x4 gt) {
;     const f32x4 u = w0 * am + w1 * a0 + w2 * ap + cbv;
;     return (f32x4){siluf_(u.x) * gt.x, siluf_(u.y) * gt.y, siluf_(u.z) * gt.z, siluf_(u.w) * gt.w};
; }
; __device__ __forceinline__ void halo_fix(const Params& p, int pm, int tid, int tail_first) {
;     ...
;     for (int q = tid; q < FFN / 4; q += NTHREADS) { const int ch = 4 * q;
;         const f32x4 w0 = *(const f32x4*)(p.conv_w + ch), w1 = *(const f32x4*)(p.conv_w + FFN + ch), w2 = *(const f32x4*)(p.conv_w + 2 * FFN + ch), cbv = *(const f32x4*)(p.conv_b + ch);
;         const f32x4 pv = (pm & 7) ? *(const f32x4*)(HB + ((size_t)(pm - 1) * 6 + 3) * FFN + ch) : z4; const f32x4 nx = ((pm & 7) != 7) ? *(const f32x4*)(HB + ((size_t)(pm + 1) * 6 + 0) * FFN + ch) : z4;
;         const f32x4 h0 = *(const f32x4*)(H + ch), h1 = *(const f32x4*)(H + FFN + ch), h2 = *(const f32x4*)(H + 2 * FFN + ch), h3 = *(const f32x4*)(H + 3 * FFN + ch), h4 = *(const f32x4*)(H + 4 * FFN + ch), h5 = *(const f32x4*)(H + 5 * FFN + ch);
;         const f32x4 rt = halo_act4(w0, w1, w2, cbv, pv, h0, h1, h4), rb = halo_act4(w0, w1, w2, cbv, h2, h3, nx, h5);
;         u32x2 ot, ob; ot.x = pk2(rt.x, rt.y); ot.y = pk2(rt.z, rt.w); ob.x = pk2(rb.x, rb.y); ob.y = pk2(rb.z, rb.w);
;         *(u32x2*)(ACT + (size_t)(pm * 256) * FFN + ch) = ot; *(u32x2*)(ACT + (size_t)(pm * 256 + 255) * FFN + ch) = ob;
;     }
	v_pk_mul_f32 v[44:45], v[18:19], v[44:45]
	v_pk_mul_f32 v[42:43], v[16:17], v[42:43]
	v_pk_mul_f32 v[18:19], v[18:19], v[48:49]
	v_pk_mul_f32 v[16:17], v[16:17], v[46:47]
	v_pk_fma_f32 v[20:21], v[8:9], v[20:21], v[42:43]
	v_pk_fma_f32 v[22:23], v[10:11], v[22:23], v[44:45]
	v_pk_fma_f32 v[10:11], v[10:11], v[52:53], v[18:19]
	v_pk_fma_f32 v[8:9], v[8:9], v[50:51], v[16:17]
	v_pk_fma_f32 v[16:17], v[6:7], v[56:57], v[22:23]
	v_pk_fma_f32 v[18:19], v[4:5], v[54:55], v[20:21]
	v_pk_fma_f32 v[6:7], v[6:7], v[14:15], v[10:11]
	v_pk_fma_f32 v[4:5], v[4:5], v[12:13], v[8:9]
	v_pk_add_f32 v[8:9], v[2:3], v[16:17]
	v_pk_add_f32 v[10:11], v[0:1], v[18:19]
	v_pk_add_f32 v[2:3], v[2:3], v[6:7]
	v_pk_add_f32 v[0:1], v[0:1], v[4:5]
	v_mul_f32_e32 v4, 0xbfb8aa3b, v10
	v_mul_f32_e32 v5, 0xbfb8aa3b, v11
	v_mul_f32_e32 v6, 0xbfb8aa3b, v8
	v_mul_f32_e32 v7, 0xbfb8aa3b, v9
	v_mul_f32_e32 v12, 0xbfb8aa3b, v0
	v_mul_f32_e32 v13, 0xbfb8aa3b, v1
	v_mul_f32_e32 v14, 0xbfb8aa3b, v2
	v_mul_f32_e32 v15, 0xbfb8aa3b, v3
	v_exp_f32_e32 v4, v4
	v_exp_f32_e32 v5, v5
	v_exp_f32_e32 v6, v6
	v_exp_f32_e32 v7, v7
	v_exp_f32_e32 v12, v12
	v_exp_f32_e32 v13, v13
	v_exp_f32_e32 v14, v14
	v_exp_f32_e32 v15, v15
	v_add_f32_e32 v4, 1.0, v4
	v_add_f32_e32 v5, 1.0, v5
	v_add_f32_e32 v6, 1.0, v6
	v_add_f32_e32 v7, 1.0, v7
	v_add_f32_e32 v12, 1.0, v12
	v_add_f32_e32 v13, 1.0, v13
	v_add_f32_e32 v14, 1.0, v14
	v_add_f32_e32 v15, 1.0, v15
	v_rcp_f32_e32 v4, v4
	v_rcp_f32_e32 v5, v5
	v_rcp_f32_e32 v6, v6
	v_rcp_f32_e32 v7, v7
	v_rcp_f32_e32 v12, v12
	v_rcp_f32_e32 v13, v13
	v_rcp_f32_e32 v14, v14
	v_rcp_f32_e32 v15, v15
	v_pk_mul_f32 v[4:5], v[10:11], v[4:5]
	v_pk_mul_f32 v[6:7], v[8:9], v[6:7]
	v_pk_mul_f32 v[0:1], v[0:1], v[12:13]
	v_pk_mul_f32 v[2:3], v[2:3], v[14:15]
	v_pk_mul_f32 v[4:5], v[58:59], v[4:5]
	v_pk_mul_f32 v[6:7], v[60:61], v[6:7]
	v_pk_mul_f32 v[0:1], v[62:63], v[0:1]
	v_pk_mul_f32 v[2:3], v[64:65], v[2:3]
	v_cvt_pk_bf16_f32 v4, v4, v5
	v_cvt_pk_bf16_f32 v5, v6, v7
	v_cvt_pk_bf16_f32 v0, v0, v1
	v_cvt_pk_bf16_f32 v1, v2, v3
	global_store_dwordx2 v[66:67], v[4:5], off
	global_store_dwordx2 v[34:35], v[0:1], off
	s_mov_b64 exec, s[80:81]
	s_waitcnt vmcnt(12)
	v_pk_mul_f32 v[144:145], v[118:119], v[144:145]
	v_pk_mul_f32 v[142:143], v[116:117], v[142:143]
	v_pk_mul_f32 v[118:119], v[118:119], v[148:149]
	v_pk_mul_f32 v[116:117], v[116:117], v[146:147]
	v_pk_fma_f32 v[120:121], v[108:109], v[120:121], v[142:143]
	v_pk_fma_f32 v[122:123], v[110:111], v[122:123], v[144:145]
	v_pk_fma_f32 v[110:111], v[110:111], v[152:153], v[118:119]
	v_pk_fma_f32 v[108:109], v[108:109], v[150:151], v[116:117]
	v_pk_fma_f32 v[116:117], v[106:107], v[156:157], v[122:123]
	v_pk_fma_f32 v[118:119], v[104:105], v[154:155], v[120:121]
	v_pk_fma_f32 v[106:107], v[106:107], v[114:115], v[110:111]
	v_pk_fma_f32 v[104:105], v[104:105], v[112:113], v[108:109]
	v_pk_add_f32 v[108:109], v[102:103], v[116:117]
	v_pk_add_f32 v[110:111], v[100:101], v[118:119]
	v_pk_add_f32 v[102:103], v[102:103], v[106:107]
	v_pk_add_f32 v[100:101], v[100:101], v[104:105]
	v_mul_f32_e32 v104, 0xbfb8aa3b, v110
	v_mul_f32_e32 v105, 0xbfb8aa3b, v111
	v_mul_f32_e32 v106, 0xbfb8aa3b, v108
	v_mul_f32_e32 v107, 0xbfb8aa3b, v109
	v_mul_f32_e32 v112, 0xbfb8aa3b, v100
	v_mul_f32_e32 v113, 0xbfb8aa3b, v101
	v_mul_f32_e32 v114, 0xbfb8aa3b, v102
	v_mul_f32_e32 v115, 0xbfb8aa3b, v103
	v_exp_f32_e32 v104, v104
	v_exp_f32_e32 v105, v105
	v_exp_f32_e32 v106, v106
	v_exp_f32_e32 v107, v107
	v_exp_f32_e32 v112, v112
	v_exp_f32_e32 v113, v113
	v_exp_f32_e32 v114, v114
	v_exp_f32_e32 v115, v115
	v_add_f32_e32 v104, 1.0, v104
	v_add_f32_e32 v105, 1.0, v105
	v_add_f32_e32 v106, 1.0, v106
	v_add_f32_e32 v107, 1.0, v107
	v_add_f32_e32 v112, 1.0, v112
	v_add_f32_e32 v113, 1.0, v113
	v_add_f32_e32 v114, 1.0, v114
	v_add_f32_e32 v115, 1.0, v115
	v_rcp_f32_e32 v104, v104
	v_rcp_f32_e32 v105, v105
	v_rcp_f32_e32 v106, v106
	v_rcp_f32_e32 v107, v107
	v_rcp_f32_e32 v112, v112
	v_rcp_f32_e32 v113, v113
	v_rcp_f32_e32 v114, v114
	v_rcp_f32_e32 v115, v115
	v_pk_mul_f32 v[104:105], v[110:111], v[104:105]
	v_pk_mul_f32 v[106:107], v[108:109], v[106:107]
	v_pk_mul_f32 v[100:101], v[100:101], v[112:113]
	v_pk_mul_f32 v[102:103], v[102:103], v[114:115]
	v_pk_mul_f32 v[104:105], v[158:159], v[104:105]
	v_pk_mul_f32 v[106:107], v[160:161], v[106:107]
	v_pk_mul_f32 v[100:101], v[162:163], v[100:101]
	v_pk_mul_f32 v[102:103], v[164:165], v[102:103]
	v_cvt_pk_bf16_f32 v104, v104, v105
	v_cvt_pk_bf16_f32 v105, v106, v107
	v_cvt_pk_bf16_f32 v100, v100, v101
	v_cvt_pk_bf16_f32 v101, v102, v103
	global_store_dwordx2 v[166:167], v[104:105], off
	global_store_dwordx2 v[134:135], v[100:101], off
	s_mov_b64 exec, s[82:83]
	s_waitcnt vmcnt(4)
; __device__ __forceinline__ unsigned pk2(float lo, float hi) { const f32x2_t v = {lo, hi}; const bf16x2_t b = __builtin_convertvector(v, bf16x2_t); return __builtin_bit_cast(unsigned, b); }
; __device__ __forceinline__ float siluf_(float x) { return x * __builtin_amdgcn_rcpf(1.0f + __expf(-x)); }
; __device__ __forceinline__ f32x4 halo_act4(const f32x4 w0, const f32x4 w1, const f32x4 w2, const f32x4 cbv, const f32x4 am, const f32x4 a0, const f32x4 ap, const f32x4 gt) {
;     const f32x4 u = w0 * am + w1 * a0 + w2 * ap + cbv;
;     return (f32x4){siluf_(u.x) * gt.x, siluf_(u.y) * gt.y, siluf_(u.z) * gt.z, siluf_(u.w) * gt.w};
; }
; __device__ __forceinline__ void halo_fix(const Params& p, int pm, int tid, int tail_first) {
;     ...
;         const f32x4 rt = halo_act4(w0, w1, w2, cbv, pv, h0, h1, h4), rb = halo_act4(w0, w1, w2, cbv, h2, h3, nx, h5);
;         u32x2 ot, ob; ot.x = pk2(rt.x, rt.y); ot.y = pk2(rt.z, rt.w); ob.x = pk2(rb.x, rb.y); ob.y = pk2(rb.z, rb.w);
;         *(u32x2*)(ACT + (size_t)(pm * 256) * FFN + ch) = ot; *(u32x2*)(ACT + (size_t)(pm * 256 + 255) * FFN + ch) = ob;
	v_pk_mul_f32 v[214:215], v[188:189], v[214:215]
	v_pk_mul_f32 v[212:213], v[186:187], v[212:213]
	v_pk_mul_f32 v[188:189], v[188:189], v[218:219]
	v_pk_mul_f32 v[186:187], v[186:187], v[216:217]
	v_pk_fma_f32 v[190:191], v[178:179], v[190:191], v[212:213]
	v_pk_fma_f32 v[192:193], v[180:181], v[192:193], v[214:215]
	v_pk_fma_f32 v[180:181], v[180:181], v[222:223], v[188:189]
	v_pk_fma_f32 v[178:179], v[178:179], v[220:221], v[186:187]
	v_pk_fma_f32 v[186:187], v[176:177], v[226:227], v[192:193]
	v_pk_fma_f32 v[188:189], v[174:175], v[224:225], v[190:191]
	v_pk_fma_f32 v[176:177], v[176:177], v[184:185], v[180:181]
	v_pk_fma_f32 v[174:175], v[174:175], v[182:183], v[178:179]
	v_pk_add_f32 v[178:179], v[172:173], v[186:187]
	v_pk_add_f32 v[180:181], v[170:171], v[188:189]
	v_pk_add_f32 v[172:173], v[172:173], v[176:177]
	v_pk_add_f32 v[170:171], v[170:171], v[174:175]
	v_mul_f32_e32 v174, 0xbfb8aa3b, v180
	v_mul_f32_e32 v175, 0xbfb8aa3b, v181
	v_mul_f32_e32 v176, 0xbfb8aa3b, v178
	v_mul_f32_e32 v177, 0xbfb8aa3b, v179
	v_mul_f32_e32 v182, 0xbfb8aa3b, v170
	v_mul_f32_e32 v183, 0xbfb8aa3b, v171
	v_mul_f32_e32 v184, 0xbfb8aa3b, v172
	v_mul_f32_e32 v185, 0xbfb8aa3b, v173
	v_exp_f32_e32 v174, v174
	v_exp_f32_e32 v175, v175
	v_exp_f32_e32 v176, v176
	v_exp_f32_e32 v177, v177
	v_exp_f32_e32 v182, v182
	v_exp_f32_e32 v183, v183
	v_exp_f32_e32 v184, v184
	v_exp_f32_e32 v185, v185
	v_add_f32_e32 v174, 1.0, v174
	v_add_f32_e32 v175, 1.0, v175
	v_add_f32_e32 v176, 1.0, v176
	v_add_f32_e32 v177, 1.0, v177
	v_add_f32_e32 v182, 1.0, v182
	v_add_f32_e32 v183, 1.0, v183
	v_add_f32_e32 v184, 1.0, v184
	v_add_f32_e32 v185, 1.0, v185
	v_rcp_f32_e32 v174, v174
	v_rcp_f32_e32 v175, v175
	v_rcp_f32_e32 v176, v176
	v_rcp_f32_e32 v177, v177
	v_rcp_f32_e32 v182, v182
	v_rcp_f32_e32 v183, v183
	v_rcp_f32_e32 v184, v184
	v_rcp_f32_e32 v185, v185
	v_pk_mul_f32 v[174:175], v[180:181], v[174:175]
	v_pk_mul_f32 v[176:177], v[178:179], v[176:177]
	v_pk_mul_f32 v[170:171], v[170:171], v[182:183]
	v_pk_mul_f32 v[172:173], v[172:173], v[184:185]
	v_pk_mul_f32 v[174:175], v[228:229], v[174:175]
	v_pk_mul_f32 v[176:177], v[230:231], v[176:177]
	v_pk_mul_f32 v[170:171], v[232:233], v[170:171]
	v_pk_mul_f32 v[172:173], v[234:235], v[172:173]
	v_cvt_pk_bf16_f32 v174, v174, v175
	v_cvt_pk_bf16_f32 v175, v176, v177
	v_cvt_pk_bf16_f32 v170, v170, v171
	v_cvt_pk_bf16_f32 v171, v172, v173
	global_store_dwordx2 v[236:237], v[174:175], off
	global_store_dwordx2 v[204:205], v[170:171], off
	s_branch .LBB0_993
; __device__ __forceinline__ unsigned pk2(float lo, float hi) { const f32x2_t v = {lo, hi}; const bf16x2_t b = __builtin_convertvector(v, bf16x2_t); return __builtin_bit_cast(unsigned, b); }
; __device__ __forceinline__ float siluf_(float x) { return x * __builtin_amdgcn_rcpf(1.0f + __expf(-x)); }
; __device__ __forceinline__ f32x4 halo_act4(const f32x4 w0, const f32x4 w1, const f32x4 w2, const f32x4 cbv, const f32x4 am, const f32x4 a0, const f32x4 ap, const f32x4 gt) {
;     const f32x4 u = w0 * am + w1 * a0 + w2 * ap + cbv;
;     return (f32x4){siluf_(u.x) * gt.x, siluf_(u.y) * gt.y, siluf_(u.z) * gt.z, siluf_(u.w) * gt.w};
; }
; __device__ __forceinline__ void halo_fix(const Params& p, int pm, int tid, int tail_first) {
;     ...
;     for (int q = tid; q < FFN / 4; q += NTHREADS) { const int ch = 4 * q;
;         const f32x4 w0 = *(const f32x4*)(p.conv_w + ch), w1 = *(const f32x4*)(p.conv_w + FFN + ch), w2 = *(const f32x4*)(p.conv_w + 2 * FFN + ch), cbv = *(const f32x4*)(p.conv_b + ch);
;         const f32x4 pv = (pm & 7) ? *(const f32x4*)(HB + ((size_t)(pm - 1) * 6 + 3) * FFN + ch) : z4; const f32x4 nx = ((pm & 7) != 7) ? *(const f32x4*)(HB + ((size_t)(pm + 1) * 6 + 0) * FFN + ch) : z4;
;         const f32x4 h0 = *(const f32x4*)(H + ch), h1 = *(const f32x4*)(H + FFN + ch), h2 = *(const f32x4*)(H + 2 * FFN + ch), h3 = *(const f32x4*)(H + 3 * FFN + ch), h4 = *(const f32x4*)(H + 4 * FFN + ch), h5 = *(const f32x4*)(H + 5 * FFN + ch);
;         const f32x4 rt = halo_act4(w0, w1, w2, cbv, pv, h0, h1, h4), rb = halo_act4(w0, w1, w2, cbv, h2, h3, nx, h5);
;         u32x2 ot, ob; ot.x = pk2(rt.x, rt.y); ot.y = pk2(rt.z, rt.w); ob.x = pk2(rb.x, rb.y); ob.y = pk2(rb.z, rb.w);
;         *(u32x2*)(ACT + (size_t)(pm * 256) * FFN + ch) = ot; *(u32x2*)(ACT + (size_t)(pm * 256 + 255) * FFN + ch) = ob;
;     }
.Lhf_c2x:
	s_mov_b64 exec, s[78:79]
	s_waitcnt vmcnt(10)
	v_pk_mul_f32 v[44:45], v[18:19], v[44:45]
	v_pk_mul_f32 v[42:43], v[16:17], v[42:43]
	v_pk_mul_f32 v[18:19], v[18:19], v[48:49]
	v_pk_mul_f32 v[16:17], v[16:17], v[46:47]
	v_pk_fma_f32 v[20:21], v[8:9], v[20:21], v[42:43]
	v_pk_fma_f32 v[22:23], v[10:11], v[22:23], v[44:45]
	v_pk_fma_f32 v[10:11], v[10:11], v[52:53], v[18:19]
	v_pk_fma_f32 v[8:9], v[8:9], v[50:51], v[16:17]
	v_pk_fma_f32 v[16:17], v[6:7], v[56:57], v[22:23]
	v_pk_fma_f32 v[18:19], v[4:5], v[54:55], v[20:21]
	v_pk_fma_f32 v[6:7], v[6:7], v[14:15], v[10:11]
	v_pk_fma_f32 v[4:5], v[4:5], v[12:13], v[8:9]
	v_pk_add_f32 v[8:9], v[2:3], v[16:17]
	v_pk_add_f32 v[10:11], v[0:1], v[18:19]
	v_pk_add_f32 v[2:3], v[2:3], v[6:7]
	v_pk_add_f32 v[0:1], v[0:1], v[4:5]
	v_mul_f32_e32 v4, 0xbfb8aa3b, v10
	v_mul_f32_e32 v5, 0xbfb8aa3b, v11
	v_mul_f32_e32 v6, 0xbfb8aa3b, v8
	v_mul_f32_e32 v7, 0xbfb8aa3b, v9
	v_mul_f32_e32 v12, 0xbfb8aa3b, v0
	v_mul_f32_e32 v13, 0xbfb8aa3b, v1
	v_mul_f32_e32 v14, 0xbfb8aa3b, v2
	v_mul_f32_e32 v15, 0xbfb8aa3b, v3
	v_exp_f32_e32 v4, v4
	v_exp_f32_e32 v5, v5
	v_exp_f32_e32 v6, v6
	v_exp_f32_e32 v7, v7
	v_exp_f32_e32 v12, v12
	v_exp_f32_e32 v13, v13
	v_exp_f32_e32 v14, v14
	v_exp_f32_e32 v15, v15
	v_add_f32_e32 v4, 1.0, v4
	v_add_f32_e32 v5, 1.0, v5
	v_add_f32_e32 v6, 1.0, v6
	v_add_f32_e32 v7, 1.0, v7
	v_add_f32_e32 v12, 1.0, v12
	v_add_f32_e32 v13, 1.0, v13
	v_add_f32_e32 v14, 1.0, v14
	v_add_f32_e32 v15, 1.0, v15
	v_rcp_f32_e32 v4, v4
	v_rcp_f32_e32 v5, v5
	v_rcp_f32_e32 v6, v6
	v_rcp_f32_e32 v7, v7
	v_rcp_f32_e32 v12, v12
	v_rcp_f32_e32 v13, v13
	v_rcp_f32_e32 v14, v14
	v_rcp_f32_e32 v15, v15
	v_pk_mul_f32 v[4:5], v[10:11], v[4:5]
	v_pk_mul_f32 v[6:7], v[8:9], v[6:7]
	v_pk_mul_f32 v[0:1], v[0:1], v[12:13]
	v_pk_mul_f32 v[2:3], v[2:3], v[14:15]
	v_pk_mul_f32 v[4:5], v[58:59], v[4:5]
	v_pk_mul_f32 v[6:7], v[60:61], v[6:7]
	v_pk_mul_f32 v[0:1], v[62:63], v[0:1]
	v_pk_mul_f32 v[2:3], v[64:65], v[2:3]
	v_cvt_pk_bf16_f32 v4, v4, v5
	v_cvt_pk_bf16_f32 v5, v6, v7
	v_cvt_pk_bf16_f32 v0, v0, v1
	v_cvt_pk_bf16_f32 v1, v2, v3
	global_store_dwordx2 v[66:67], v[4:5], off
	global_store_dwordx2 v[34:35], v[0:1], off
	s_mov_b64 exec, s[80:81]
	s_waitcnt vmcnt(2)
	v_pk_mul_f32 v[144:145], v[118:119], v[144:145]
	v_pk_mul_f32 v[142:143], v[116:117], v[142:143]
	v_pk_mul_f32 v[118:119], v[118:119], v[148:149]
	v_pk_mul_f32 v[116:117], v[116:117], v[146:147]
	v_pk_fma_f32 v[120:121], v[108:109], v[120:121], v[142:143]
	v_pk_fma_f32 v[122:123], v[110:111], v[122:123], v[144:145]
	v_pk_fma_f32 v[110:111], v[110:111], v[152:153], v[118:119]
	v_pk_fma_f32 v[108:109], v[108:109], v[150:151], v[116:117]
	v_pk_fma_f32 v[116:117], v[106:107], v[156:157], v[122:123]
	v_pk_fma_f32 v[118:119], v[104:105], v[154:155], v[120:121]
	v_pk_fma_f32 v[106:107], v[106:107], v[114:115], v[110:111]
	v_pk_fma_f32 v[104:105], v[104:105], v[112:113], v[108:109]
	v_pk_add_f32 v[108:109], v[102:103], v[116:117]
	v_pk_add_f32 v[110:111], v[100:101], v[118:119]
	v_pk_add_f32 v[102:103], v[102:103], v[106:107]
	v_pk_add_f32 v[100:101], v[100:101], v[104:105]
	v_mul_f32_e32 v104, 0xbfb8aa3b, v110
	v_mul_f32_e32 v105, 0xbfb8aa3b, v111
	v_mul_f32_e32 v106, 0xbfb8aa3b, v108
	v_mul_f32_e32 v107, 0xbfb8aa3b, v109
	v_mul_f32_e32 v112, 0xbfb8aa3b, v100
	v_mul_f32_e32 v113, 0xbfb8aa3b, v101
	v_mul_f32_e32 v114, 0xbfb8aa3b, v102
	v_mul_f32_e32 v115, 0xbfb8aa3b, v103
	v_exp_f32_e32 v104, v104
	v_exp_f32_e32 v105, v105
	v_exp_f32_e32 v106, v106
	v_exp_f32_e32 v107, v107
	v_exp_f32_e32 v112, v112
	v_exp_f32_e32 v113, v113
	v_exp_f32_e32 v114, v114
	v_exp_f32_e32 v115, v115
	v_add_f32_e32 v104, 1.0, v104
	v_add_f32_e32 v105, 1.0, v105
	v_add_f32_e32 v106, 1.0, v106
	v_add_f32_e32 v107, 1.0, v107
	v_add_f32_e32 v112, 1.0, v112
	v_add_f32_e32 v113, 1.0, v113
	v_add_f32_e32 v114, 1.0, v114
	v_add_f32_e32 v115, 1.0, v115
	v_rcp_f32_e32 v104, v104
	v_rcp_f32_e32 v105, v105
	v_rcp_f32_e32 v106, v106
	v_rcp_f32_e32 v107, v107
	v_rcp_f32_e32 v112, v112
	v_rcp_f32_e32 v113, v113
	v_rcp_f32_e32 v114, v114
	v_rcp_f32_e32 v115, v115
	v_pk_mul_f32 v[104:105], v[110:111], v[104:105]
	v_pk_mul_f32 v[106:107], v[108:109], v[106:107]
	v_pk_mul_f32 v[100:101], v[100:101], v[112:113]
	v_pk_mul_f32 v[102:103], v[102:103], v[114:115]
	v_pk_mul_f32 v[104:105], v[158:159], v[104:105]
	v_pk_mul_f32 v[106:107], v[160:161], v[106:107]
	v_pk_mul_f32 v[100:101], v[162:163], v[100:101]
	v_pk_mul_f32 v[102:103], v[164:165], v[102:103]
	v_cvt_pk_bf16_f32 v104, v104, v105
	v_cvt_pk_bf16_f32 v105, v106, v107
	v_cvt_pk_bf16_f32 v100, v100, v101
	v_cvt_pk_bf16_f32 v101, v102, v103
	global_store_dwordx2 v[166:167], v[104:105], off
	global_store_dwordx2 v[134:135], v[100:101], off
	s_branch .LBB0_993
.Lhf_c1x:
	s_mov_b64 exec, s[78:79]
	s_waitcnt vmcnt(0)
	v_pk_mul_f32 v[44:45], v[18:19], v[44:45]
	v_pk_mul_f32 v[42:43], v[16:17], v[42:43]
	v_pk_mul_f32 v[18:19], v[18:19], v[48:49]
	v_pk_mul_f32 v[16:17], v[16:17], v[46:47]
	v_pk_fma_f32 v[20:21], v[8:9], v[20:21], v[42:43]
	v_pk_fma_f32 v[22:23], v[10:11], v[22:23], v[44:45]
	v_pk_fma_f32 v[10:11], v[10:11], v[52:53], v[18:19]
	v_pk_fma_f32 v[8:9], v[8:9], v[50:51], v[16:17]
	v_pk_fma_f32 v[16:17], v[6:7], v[56:57], v[22:23]
	v_pk_fma_f32 v[18:19], v[4:5], v[54:55], v[20:21]
	v_pk_fma_f32 v[6:7], v[6:7], v[14:15], v[10:11]
	v_pk_fma_f32 v[4:5], v[4:5], v[12:13], v[8:9]
	v_pk_add_f32 v[8:9], v[2:3], v[16:17]
	v_pk_add_f32 v[10:11], v[0:1], v[18:19]
	v_pk_add_f32 v[2:3], v[2:3], v[6:7]
	v_pk_add_f32 v[0:1], v[0:1], v[4:5]
	v_mul_f32_e32 v4, 0xbfb8aa3b, v10
	v_mul_f32_e32 v5, 0xbfb8aa3b, v11
	v_mul_f32_e32 v6, 0xbfb8aa3b, v8
	v_mul_f32_e32 v7, 0xbfb8aa3b, v9
	v_mul_f32_e32 v12, 0xbfb8aa3b, v0
	v_mul_f32_e32 v13, 0xbfb8aa3b, v1
	v_mul_f32_e32 v14, 0xbfb8aa3b, v2
	v_mul_f32_e32 v15, 0xbfb8aa3b, v3
	v_exp_f32_e32 v4, v4
	v_exp_f32_e32 v5, v5
	v_exp_f32_e32 v6, v6
	v_exp_f32_e32 v7, v7
	v_exp_f32_e32 v12, v12
	v_exp_f32_e32 v13, v13
	v_exp_f32_e32 v14, v14
	v_exp_f32_e32 v15, v15
	v_add_f32_e32 v4, 1.0, v4
	v_add_f32_e32 v5, 1.0, v5
	v_add_f32_e32 v6, 1.0, v6
	v_add_f32_e32 v7, 1.0, v7
	v_add_f32_e32 v12, 1.0, v12
	v_add_f32_e32 v13, 1.0, v13
	v_add_f32_e32 v14, 1.0, v14
	v_add_f32_e32 v15, 1.0, v15
	v_rcp_f32_e32 v4, v4
	v_rcp_f32_e32 v5, v5
	v_rcp_f32_e32 v6, v6
	v_rcp_f32_e32 v7, v7
	v_rcp_f32_e32 v12, v12
	v_rcp_f32_e32 v13, v13
	v_rcp_f32_e32 v14, v14
	v_rcp_f32_e32 v15, v15
	v_pk_mul_f32 v[4:5], v[10:11], v[4:5]
	v_pk_mul_f32 v[6:7], v[8:9], v[6:7]
	v_pk_mul_f32 v[0:1], v[0:1], v[12:13]
	v_pk_mul_f32 v[2:3], v[2:3], v[14:15]
	v_pk_mul_f32 v[4:5], v[58:59], v[4:5]
	v_pk_mul_f32 v[6:7], v[60:61], v[6:7]
	v_pk_mul_f32 v[0:1], v[62:63], v[0:1]
	v_pk_mul_f32 v[2:3], v[64:65], v[2:3]
	v_cvt_pk_bf16_f32 v4, v4, v5
	v_cvt_pk_bf16_f32 v5, v6, v7
	v_cvt_pk_bf16_f32 v0, v0, v1
	v_cvt_pk_bf16_f32 v1, v2, v3
	global_store_dwordx2 v[66:67], v[4:5], off
	global_store_dwordx2 v[34:35], v[0:1], off
